# baseline (speedup 1.0000x reference)
; #define PG8_STAGE(bufoff, gbase, voff) do { _Pragma("unroll") for (int _i = 0; _i < 2; ++_i) \
;         __builtin_amdgcn_global_load_lds((const unsigned*)((const char*)(gbase) + (voff)[_i]), (PG8_LAS unsigned*)(lds + (bufoff) + ldsw + _i * 8192), 16, 0, 0); } while (0)
; #define PG8_WAIT_V(n) asm volatile("s_waitcnt vmcnt(" #n ")" ::: "memory")
; #define PG8_BAR __builtin_amdgcn_s_barrier()
; template <class Epi, class Sched, bool ALIGN_EPI = false, bool SP2 = false>
; __device__ __forceinline__ void gemm_phase(PG8_LAS unsigned char* lds, const Gemm g, const Sched& S, const Epi& E) {
;     const int tid = threadIdx.x, wid = __builtin_amdgcn_readfirstlane(tid >> 6), lane = tid & 63, wr = wid >> 2, wc = wid & 3, fr = lane & 15, fq = lane >> 4;
;     const int K = g.K;
;     unsigned voffA[2], voffB[2];
; #pragma unroll
;     for (int i = 0; i < 2; ++i) { int R, C; stage_rc(tid * 16 + i * 8192, R, C); const int Rb = Epi::PERM ? ((R & ~31) + perm32(R & 31)) : R;
;         voffA[i] = (unsigned)(R * K + C) * 2u; voffB[i] = (unsigned)(Rb * K + C) * 2u; }
;     const long kstep = (long)(BK * 2);
;     long ks = kstep;
;     const size_t hstep = (size_t)HALF * K * 2;
;     const size_t tstep = 2 * hstep;
;     const unsigned ldsw = (unsigned)wid * 1024u;
;     const int aoff = lds_byte(wr * 64 + fr, fq * 8), boff = lds_byte(wc * 32 + fr, fq * 8);
;     ...
;         PG8_STAGE(PG8_SB(0, 0), cB, voffB); PG8_STAGE(PG8_SB(0, 1), cB + hstep, voffB); PG8_STAGE(PG8_SA(0, 0), cA, voffA); PG8_STAGE(PG8_SA(0, 1), cA + hstep, voffA);
;         if (wr == 1) PG8_BAR;
;         PG8_WAIT_V(2); PG8_BAR;
;         PG8_STAGE(PG8_SB(1, 0), cB + kstep, voffB); PG8_STAGE(PG8_SA(1, 0), cA + kstep, voffA); PG8_STAGE(PG8_SB(1, 1), cB + hstep + kstep, voffB);
;         PG8_WAIT_V(6); PG8_BAR;
.LBB0_343:
	s_lshl_b32 s4, s19, 5
	s_xor_b64 s[26:27], s[26:27], -1
	s_lshl_b32 s33, s18, 13
	s_and_b32 s19, s4, 0x60
	s_add_u32 s70, s58, 0x1b800000
	s_mov_b64 s[44:45], 0x80
	s_addc_u32 s71, s59, 0
	s_add_i32 m0, s98, 0x18000
	v_lshl_add_u64 v[10:11], v[10:11], 0, s[44:45]
	s_waitcnt vmcnt(2)
	s_barrier
	global_load_lds_dwordx4 v[10:11], off
	v_lshl_add_u64 v[6:7], v[6:7], 0, s[44:45]
	s_add_i32 m0, s98, 0x1a000
	s_add_i32 s72, s98, 0x8000
	global_load_lds_dwordx4 v[6:7], off
	s_add_i32 s73, s98, 0xa000
	v_lshl_add_u64 v[4:5], v[4:5], 0, s[44:45]
	s_add_i32 m0, s98, 0x1c000
	v_lshl_add_u64 v[2:3], v[2:3], 0, s[44:45]
	global_load_lds_dwordx4 v[4:5], off
	s_add_i32 m0, s98, 0x1e000
	s_cmpk_lt_u32 s5, 0x100
	global_load_lds_dwordx4 v[2:3], off
	v_mul_f32_e32 v3, v16, v17
	v_trunc_f32_e32 v3, v3
	v_cvt_u32_f32_e32 v4, v3
	v_fma_f32 v3, -v3, v15, v16
	s_cselect_b64 s[28:29], -1, 0
	s_lshr_b32 s91, s79, s12
	s_lshr_b32 s75, s52, 3
	v_cmp_ge_f32_e64 s[4:5], |v3|, v15
	v_readfirstlane_b32 s12, v4
	s_cmp_lg_u64 s[4:5], 0
	s_addc_u32 s4, s12, 0
	s_and_b32 s76, s4, 0x7ff
	v_cvt_f32_u32_e32 v3, s76
	v_lshlrev_b32_e32 v4, 2, v197
	v_lshl_or_b32 v2, v197, 6, v198
	v_and_b32_e32 v4, 32, v4
	v_bitop3_b32 v4, v2, s33, v4 bitop3:0xde
	v_rcp_iflag_f32_e32 v2, v3
	v_rcp_iflag_f32_e32 v3, v18
	s_sub_i32 s4, 0, s76
	s_waitcnt vmcnt(4)
	v_mul_f32_e32 v2, 0x4f7ffffe, v2
	v_cvt_u32_f32_e32 v2, v2
	v_lshl_or_b32 v144, s18, 6, v197
	v_lshl_or_b32 v145, s19, 7, v199
	v_add_u32_e32 v242, 0x10000, v145
	v_or_b32_e32 v146, s19, v192
	v_readfirstlane_b32 s5, v2
	v_mul_f32_e32 v2, 0x4f7ffffe, v14
	v_cvt_u32_f32_e32 v2, v2
	s_mul_i32 s4, s4, s5
	s_mul_hi_u32 s4, s5, s4
	s_add_i32 s77, s5, s4
	v_readfirstlane_b32 s5, v2
	v_mul_f32_e32 v2, 0x4f7ffffe, v3
	v_cvt_u32_f32_e32 v2, v2
	s_sub_i32 s4, 0, s7
	s_mul_i32 s4, s4, s5
	s_mul_hi_u32 s4, s5, s4
	s_add_i32 s69, s5, s4
	s_sub_i32 s4, 0, s78
	v_readfirstlane_b32 s5, v2
	s_mul_i32 s4, s4, s5
	v_add_lshl_u32 v2, v200, v19, 1
	v_mov_b32_e32 v3, v1
	s_mul_hi_u32 s4, s5, s4
	v_lshl_add_u64 v[136:137], s[16:17], 0, v[2:3]
	v_add_lshl_u32 v2, v200, v20, 1
	s_mov_b32 s18, 0
	s_add_i32 s5, s5, s4
	v_lshl_add_u64 v[138:139], s[16:17], 0, v[2:3]
	v_add_u32_e32 v147, 0, v4
	s_barrier
	s_branch .LBB0_346

; #define PG8_STAGE(bufoff, gbase, voff) do { _Pragma("unroll") for (int _i = 0; _i < 2; ++_i) \
;         __builtin_amdgcn_global_load_lds((const unsigned*)((const char*)(gbase) + (voff)[_i]), (PG8_LAS unsigned*)(lds + (bufoff) + ldsw + _i * 8192), 16, 0, 0); } while (0)
; #define PG8_LDA(dst, b, h) do { _Pragma("unroll") for (int m = 0; m < 4; ++m) _Pragma("unroll") for (int k = 0; k < 2; ++k) dst[m][k] = *(const PG8_LAS bf16x8*)(lds + PG8_SA(b, h) + aoff + m * 2048 + k * 1024); } while (0)
; #define PG8_LDB(dst, b, h) do { _Pragma("unroll") for (int n = 0; n < 2; ++n) _Pragma("unroll") for (int k = 0; k < 2; ++k) dst[n][k] = *(const PG8_LAS bf16x8*)(lds + PG8_SB(b, h) + boff + n * 2048 + k * 1024); } while (0)
; #define PG8_MMA(ai, bj, At, Bt) do { __builtin_amdgcn_s_setprio(1); _Pragma("unroll") for (int m = 0; m < 4; ++m) _Pragma("unroll") for (int n = 0; n < 2; ++n) _Pragma("unroll") for (int k = 0; k < 2; ++k) \
;         acc[ai][bj][m][n] = __builtin_amdgcn_mfma_f32_16x16x32_bf16(Bt[n][k], At[m][k], acc[ai][bj][m][n], 0, 0, 0); __builtin_amdgcn_s_setprio(0); } while (0)
; #define PG8_WAIT_V(n) asm volatile("s_waitcnt vmcnt(" #n ")" ::: "memory")
; #define PG8_WAIT_L(n) asm volatile("s_waitcnt lgkmcnt(" #n ")" ::: "memory")
; #define PG8_BAR __builtin_amdgcn_s_barrier()
; #define PG8_SCHED __builtin_amdgcn_sched_barrier(0)
; template <class Epi, class Sched, bool ALIGN_EPI = false, bool SP2 = false>
; __device__ __forceinline__ void gemm_phase(PG8_LAS unsigned char* lds, const Gemm g, const Sched& S, const Epi& E) {
;     ...
;             PG8_LDB(B0, 0, 0); PG8_LDB(B1, 0, 1); PG8_SCHED; PG8_LDA(At, 0, 0); PG8_STAGE(PG8_SA(1, 1), a1 + hstep, voffA);
;             PG8_WAIT_V(8); PG8_WAIT_L(0); PG8_BAR; PG8_MMA(0, 0, At, B0); PG8_MMA(0, 1, At, B1); PG8_BAR; PG8_SCHED;
;             PG8_LDA(At, 0, 1); PG8_STAGE(PG8_SB(0, 0), b2, voffB); PG8_STAGE(PG8_SB(0, 1), b2 + hstep, voffB); PG8_STAGE(PG8_SA(0, 0), a2, voffA);
;             PG8_WAIT_V(8); PG8_WAIT_L(0); PG8_BAR; PG8_MMA(1, 0, At, B0); PG8_MMA(1, 1, At, B1); PG8_BAR; PG8_SCHED;
.Lgemm_head:
	ds_read_b128 v[148:151], v242
	ds_read_b128 v[152:155], v242 offset:1024
	ds_read_b128 v[156:159], v242 offset:2048
	ds_read_b128 v[160:163], v242 offset:3072
	ds_read_b128 v[164:167], v242 offset:16384
	ds_read_b128 v[168:171], v242 offset:17408
	ds_read_b128 v[172:175], v242 offset:18432
	ds_read_b128 v[176:179], v242 offset:19456
	s_sub_u32 s38, s18, s44
	s_subb_u32 s39, s19, s45
	ds_read_b128 v[182:185], v147
	ds_read_b128 v[186:189], v147 offset:1024
	ds_read_b128 v[208:211], v147 offset:2048
	ds_read_b128 v[212:215], v147 offset:3072
	ds_read_b128 v[216:219], v147 offset:4096
	ds_read_b128 v[220:223], v147 offset:5120
	ds_read_b128 v[224:227], v147 offset:6144
	ds_read_b128 v[228:231], v147 offset:7168
	s_add_u32 s38, s38, s50
	s_addc_u32 s39, s39, s51
	s_mov_b32 m0, s72
	s_nop 0
	global_load_lds_dwordx4 v130, s[38:39]
	s_mov_b32 m0, s73
	s_nop 0
	global_load_lds_dwordx4 v132, s[38:39]
	s_add_i32 m0, s98, 0xc000
	s_add_u32 s38, s38, s16
	s_addc_u32 s39, s39, 0
	global_load_lds_dwordx4 v130, s[38:39]
	s_add_i32 m0, s98, 0xe000
	s_nop 0
	global_load_lds_dwordx4 v132, s[38:39]
	s_waitcnt vmcnt(8)
	s_waitcnt lgkmcnt(0)
	s_barrier
	s_setprio 1
	s_waitcnt lgkmcnt(0)
	v_mfma_f32_16x16x32_bf16 v[126:129], v[148:151], v[182:185], v[126:129]
	v_mfma_f32_16x16x32_bf16 v[122:125], v[156:159], v[182:185], v[122:125]
	v_mfma_f32_16x16x32_bf16 v[118:121], v[148:151], v[208:211], v[118:121]
	v_mfma_f32_16x16x32_bf16 v[110:113], v[156:159], v[208:211], v[110:113]
	v_mfma_f32_16x16x32_bf16 v[102:105], v[148:151], v[216:219], v[102:105]
	v_mfma_f32_16x16x32_bf16 v[94:97], v[156:159], v[216:219], v[94:97]
	v_mfma_f32_16x16x32_bf16 v[86:89], v[148:151], v[224:227], v[86:89]
	v_mfma_f32_16x16x32_bf16 v[78:81], v[156:159], v[224:227], v[78:81]
	v_mfma_f32_16x16x32_bf16 v[126:129], v[152:155], v[186:189], v[126:129]
	v_mfma_f32_16x16x32_bf16 v[122:125], v[160:163], v[186:189], v[122:125]
	v_mfma_f32_16x16x32_bf16 v[118:121], v[152:155], v[212:215], v[118:121]
	v_mfma_f32_16x16x32_bf16 v[110:113], v[160:163], v[212:215], v[110:113]
	v_mfma_f32_16x16x32_bf16 v[102:105], v[152:155], v[220:223], v[102:105]
	v_mfma_f32_16x16x32_bf16 v[94:97], v[160:163], v[220:223], v[94:97]
	v_mfma_f32_16x16x32_bf16 v[86:89], v[152:155], v[228:231], v[86:89]
	v_mfma_f32_16x16x32_bf16 v[78:81], v[160:163], v[228:231], v[78:81]
	s_setprio 0
	s_setprio 1
	v_mfma_f32_16x16x32_bf16 v[114:117], v[164:167], v[182:185], v[114:117]
	v_mfma_f32_16x16x32_bf16 v[106:109], v[172:175], v[182:185], v[106:109]
	v_mfma_f32_16x16x32_bf16 v[98:101], v[164:167], v[208:211], v[98:101]
	v_mfma_f32_16x16x32_bf16 v[90:93], v[172:175], v[208:211], v[90:93]
	v_mfma_f32_16x16x32_bf16 v[82:85], v[164:167], v[216:219], v[82:85]
	v_mfma_f32_16x16x32_bf16 v[74:77], v[172:175], v[216:219], v[74:77]
	v_mfma_f32_16x16x32_bf16 v[70:73], v[164:167], v[224:227], v[70:73]
	v_mfma_f32_16x16x32_bf16 v[66:69], v[172:175], v[224:227], v[66:69]
	v_mfma_f32_16x16x32_bf16 v[114:117], v[168:171], v[186:189], v[114:117]
	v_mfma_f32_16x16x32_bf16 v[106:109], v[176:179], v[186:189], v[106:109]
	v_mfma_f32_16x16x32_bf16 v[98:101], v[168:171], v[212:215], v[98:101]
	v_mfma_f32_16x16x32_bf16 v[90:93], v[176:179], v[212:215], v[90:93]
	v_mfma_f32_16x16x32_bf16 v[82:85], v[168:171], v[220:223], v[82:85]
	v_mfma_f32_16x16x32_bf16 v[74:77], v[176:179], v[220:223], v[74:77]
	v_mfma_f32_16x16x32_bf16 v[70:73], v[168:171], v[228:231], v[70:73]
	v_mfma_f32_16x16x32_bf16 v[66:69], v[176:179], v[228:231], v[66:69]
	s_setprio 0
	s_barrier
	s_add_i32 m0, s97, 0x10000
	ds_read_b128 v[182:185], v147 offset:16384
	ds_read_b128 v[186:189], v147 offset:17408
	ds_read_b128 v[208:211], v147 offset:18432
	ds_read_b128 v[212:215], v147 offset:19456
	ds_read_b128 v[216:219], v147 offset:20480
	ds_read_b128 v[220:223], v147 offset:21504
	ds_read_b128 v[224:227], v147 offset:22528
	ds_read_b128 v[228:231], v147 offset:23552
	global_load_lds_dwordx4 v0, s[56:57]
	s_add_i32 m0, s97, 0x12000
	s_add_u32 s38, s56, s16
	s_addc_u32 s39, s57, 0
	global_load_lds_dwordx4 v134, s[56:57]
	s_add_i32 m0, s97, 0x14000
	s_nop 0
	global_load_lds_dwordx4 v0, s[38:39]
	s_add_i32 m0, s97, 0x16000
	s_nop 0
	global_load_lds_dwordx4 v134, s[38:39]
	s_waitcnt vmcnt(6)
	s_waitcnt lgkmcnt(0)
	s_barrier
	s_setprio 1
	s_waitcnt lgkmcnt(0)
	v_mfma_f32_16x16x32_bf16 v[62:65], v[148:151], v[182:185], v[62:65]
	v_mfma_f32_16x16x32_bf16 v[58:61], v[156:159], v[182:185], v[58:61]
	v_mfma_f32_16x16x32_bf16 v[54:57], v[148:151], v[208:211], v[54:57]
	v_mfma_f32_16x16x32_bf16 v[46:49], v[156:159], v[208:211], v[46:49]
	v_mfma_f32_16x16x32_bf16 v[38:41], v[148:151], v[216:219], v[38:41]
	v_mfma_f32_16x16x32_bf16 v[30:33], v[156:159], v[216:219], v[30:33]
	v_mfma_f32_16x16x32_bf16 v[22:25], v[148:151], v[224:227], v[22:25]
	v_mfma_f32_16x16x32_bf16 v[14:17], v[156:159], v[224:227], v[14:17]
	v_mfma_f32_16x16x32_bf16 v[62:65], v[152:155], v[186:189], v[62:65]
	v_mfma_f32_16x16x32_bf16 v[58:61], v[160:163], v[186:189], v[58:61]
	v_mfma_f32_16x16x32_bf16 v[54:57], v[152:155], v[212:215], v[54:57]
	v_mfma_f32_16x16x32_bf16 v[46:49], v[160:163], v[212:215], v[46:49]
	v_mfma_f32_16x16x32_bf16 v[38:41], v[152:155], v[220:223], v[38:41]
	v_mfma_f32_16x16x32_bf16 v[30:33], v[160:163], v[220:223], v[30:33]
	v_mfma_f32_16x16x32_bf16 v[22:25], v[152:155], v[228:231], v[22:25]
	v_mfma_f32_16x16x32_bf16 v[14:17], v[160:163], v[228:231], v[14:17]
	s_setprio 0
	s_setprio 1
	v_mfma_f32_16x16x32_bf16 v[50:53], v[164:167], v[182:185], v[50:53]
	v_mfma_f32_16x16x32_bf16 v[42:45], v[172:175], v[182:185], v[42:45]
	v_mfma_f32_16x16x32_bf16 v[34:37], v[164:167], v[208:211], v[34:37]
	v_mfma_f32_16x16x32_bf16 v[26:29], v[172:175], v[208:211], v[26:29]
	v_mfma_f32_16x16x32_bf16 v[18:21], v[164:167], v[216:219], v[18:21]
	v_mfma_f32_16x16x32_bf16 v[10:13], v[172:175], v[216:219], v[10:13]
	v_mfma_f32_16x16x32_bf16 v[6:9], v[164:167], v[224:227], v[6:9]
	v_mfma_f32_16x16x32_bf16 v[2:5], v[172:175], v[224:227], v[2:5]
	v_mfma_f32_16x16x32_bf16 v[50:53], v[168:171], v[186:189], v[50:53]
	v_mfma_f32_16x16x32_bf16 v[42:45], v[176:179], v[186:189], v[42:45]
	v_mfma_f32_16x16x32_bf16 v[34:37], v[168:171], v[212:215], v[34:37]
	v_mfma_f32_16x16x32_bf16 v[26:29], v[176:179], v[212:215], v[26:29]
	v_mfma_f32_16x16x32_bf16 v[18:21], v[168:171], v[220:223], v[18:21]
	v_mfma_f32_16x16x32_bf16 v[10:13], v[176:179], v[220:223], v[10:13]
	v_mfma_f32_16x16x32_bf16 v[6:9], v[168:171], v[228:231], v[6:9]
	v_mfma_f32_16x16x32_bf16 v[2:5], v[176:179], v[228:231], v[2:5]
	s_setprio 0
	s_barrier
; #define PG8_STAGE(bufoff, gbase, voff) do { _Pragma("unroll") for (int _i = 0; _i < 2; ++_i) \
;         __builtin_amdgcn_global_load_lds((const unsigned*)((const char*)(gbase) + (voff)[_i]), (PG8_LAS unsigned*)(lds + (bufoff) + ldsw + _i * 8192), 16, 0, 0); } while (0)
; #define PG8_LDA(dst, b, h) do { _Pragma("unroll") for (int m = 0; m < 4; ++m) _Pragma("unroll") for (int k = 0; k < 2; ++k) dst[m][k] = *(const PG8_LAS bf16x8*)(lds + PG8_SA(b, h) + aoff + m * 2048 + k * 1024); } while (0)
; #define PG8_LDB(dst, b, h) do { _Pragma("unroll") for (int n = 0; n < 2; ++n) _Pragma("unroll") for (int k = 0; k < 2; ++k) dst[n][k] = *(const PG8_LAS bf16x8*)(lds + PG8_SB(b, h) + boff + n * 2048 + k * 1024); } while (0)
; #define PG8_MMA(ai, bj, At, Bt) do { __builtin_amdgcn_s_setprio(1); _Pragma("unroll") for (int m = 0; m < 4; ++m) _Pragma("unroll") for (int n = 0; n < 2; ++n) _Pragma("unroll") for (int k = 0; k < 2; ++k) \
;         acc[ai][bj][m][n] = __builtin_amdgcn_mfma_f32_16x16x32_bf16(Bt[n][k], At[m][k], acc[ai][bj][m][n], 0, 0, 0); __builtin_amdgcn_s_setprio(0); } while (0)
; #define PG8_WAIT_V(n) asm volatile("s_waitcnt vmcnt(" #n ")" ::: "memory")
; #define PG8_WAIT_L(n) asm volatile("s_waitcnt lgkmcnt(" #n ")" ::: "memory")
; #define PG8_BAR __builtin_amdgcn_s_barrier()
; template <class Epi, class Sched, bool ALIGN_EPI = false, bool SP2 = false>
; __device__ __forceinline__ void gemm_phase(PG8_LAS unsigned char* lds, const Gemm g, const Sched& S, const Epi& E) {
;     ...
;         for (int t = 0; t < nt; t += 2) {
;             const bool last = (t == nt - 2);
;             const char* a1 = cA + (long)(t + 1) * ks;
;             const char* a2 = last ? nA : cA + (long)(t + 2) * ks; const char* b2 = last ? nB : cB + (long)(t + 2) * ks;
;             const long ks3 = last ? nks : ks; const char* a3 = a2 + ks3; const char* b3 = b2 + ks3;
;     ...
;             PG8_LDB(B0, 1, 0); PG8_LDB(B1, 1, 1); PG8_SCHED; PG8_LDA(At, 1, 0); PG8_STAGE(PG8_SA(0, 1), a2 + hstep, voffA);
;             PG8_WAIT_V(8); PG8_WAIT_L(0); PG8_BAR; PG8_MMA(0, 0, At, B0); PG8_MMA(0, 1, At, B1); PG8_BAR; PG8_SCHED;
;             PG8_LDA(At, 1, 1); PG8_STAGE(PG8_SB(1, 0), b3, voffB); PG8_STAGE(PG8_SB(1, 1), b3 + hstep, voffB); PG8_STAGE(PG8_SA(1, 0), a3, voffA);
;             PG8_WAIT_V(8); PG8_WAIT_L(0); PG8_BAR; PG8_MMA(1, 0, At, B0); PG8_MMA(1, 1, At, B1); PG8_BAR; PG8_SCHED;
	ds_read_b128 v[148:151], v242 offset:32768
	ds_read_b128 v[152:155], v242 offset:33792
	ds_read_b128 v[156:159], v242 offset:34816
	ds_read_b128 v[160:163], v242 offset:35840
	ds_read_b128 v[164:167], v242 offset:49152
	ds_read_b128 v[168:171], v242 offset:50176
	ds_read_b128 v[172:175], v242 offset:51200
	ds_read_b128 v[176:179], v242 offset:52224
	s_mov_b32 m0, s98
	ds_read_b128 v[182:185], v147 offset:32768
	ds_read_b128 v[186:189], v147 offset:33792
	ds_read_b128 v[208:211], v147 offset:34816
	ds_read_b128 v[212:215], v147 offset:35840
	ds_read_b128 v[216:219], v147 offset:36864
	ds_read_b128 v[220:223], v147 offset:37888
	ds_read_b128 v[224:227], v147 offset:38912
	ds_read_b128 v[228:231], v147 offset:39936
	global_load_lds_dwordx4 v130, s[62:63]
	s_mov_b32 m0, s99
	s_add_u32 s38, s62, s16
	s_addc_u32 s39, s63, 0
	global_load_lds_dwordx4 v132, s[62:63]
	s_mov_b32 m0, s68
	s_nop 0
	global_load_lds_dwordx4 v130, s[38:39]
	s_mov_b32 m0, s64
	s_nop 0
	global_load_lds_dwordx4 v132, s[38:39]
	s_waitcnt vmcnt(8)
	s_waitcnt lgkmcnt(0)
	s_barrier
	s_setprio 1
	s_waitcnt lgkmcnt(0)
	v_mfma_f32_16x16x32_bf16 v[126:129], v[148:151], v[182:185], v[126:129]
	v_mfma_f32_16x16x32_bf16 v[122:125], v[156:159], v[182:185], v[122:125]
	v_mfma_f32_16x16x32_bf16 v[118:121], v[148:151], v[208:211], v[118:121]
	v_mfma_f32_16x16x32_bf16 v[110:113], v[156:159], v[208:211], v[110:113]
	v_mfma_f32_16x16x32_bf16 v[102:105], v[148:151], v[216:219], v[102:105]
	v_mfma_f32_16x16x32_bf16 v[94:97], v[156:159], v[216:219], v[94:97]
	v_mfma_f32_16x16x32_bf16 v[86:89], v[148:151], v[224:227], v[86:89]
	v_mfma_f32_16x16x32_bf16 v[78:81], v[156:159], v[224:227], v[78:81]
	v_mfma_f32_16x16x32_bf16 v[126:129], v[152:155], v[186:189], v[126:129]
	v_mfma_f32_16x16x32_bf16 v[122:125], v[160:163], v[186:189], v[122:125]
	v_mfma_f32_16x16x32_bf16 v[118:121], v[152:155], v[212:215], v[118:121]
	v_mfma_f32_16x16x32_bf16 v[110:113], v[160:163], v[212:215], v[110:113]
	v_mfma_f32_16x16x32_bf16 v[102:105], v[152:155], v[220:223], v[102:105]
	v_mfma_f32_16x16x32_bf16 v[94:97], v[160:163], v[220:223], v[94:97]
	v_mfma_f32_16x16x32_bf16 v[86:89], v[152:155], v[228:231], v[86:89]
	v_mfma_f32_16x16x32_bf16 v[78:81], v[160:163], v[228:231], v[78:81]
	s_setprio 0
	s_setprio 1
	v_mfma_f32_16x16x32_bf16 v[114:117], v[164:167], v[182:185], v[114:117]
	v_mfma_f32_16x16x32_bf16 v[106:109], v[172:175], v[182:185], v[106:109]
	v_mfma_f32_16x16x32_bf16 v[98:101], v[164:167], v[208:211], v[98:101]
	v_mfma_f32_16x16x32_bf16 v[90:93], v[172:175], v[208:211], v[90:93]
	v_mfma_f32_16x16x32_bf16 v[82:85], v[164:167], v[216:219], v[82:85]
	v_mfma_f32_16x16x32_bf16 v[74:77], v[172:175], v[216:219], v[74:77]
	v_mfma_f32_16x16x32_bf16 v[70:73], v[164:167], v[224:227], v[70:73]
	v_mfma_f32_16x16x32_bf16 v[66:69], v[172:175], v[224:227], v[66:69]
	v_mfma_f32_16x16x32_bf16 v[114:117], v[168:171], v[186:189], v[114:117]
	v_mfma_f32_16x16x32_bf16 v[106:109], v[176:179], v[186:189], v[106:109]
	v_mfma_f32_16x16x32_bf16 v[98:101], v[168:171], v[212:215], v[98:101]
	v_mfma_f32_16x16x32_bf16 v[90:93], v[176:179], v[212:215], v[90:93]
	v_mfma_f32_16x16x32_bf16 v[82:85], v[168:171], v[220:223], v[82:85]
	v_mfma_f32_16x16x32_bf16 v[74:77], v[176:179], v[220:223], v[74:77]
	v_mfma_f32_16x16x32_bf16 v[70:73], v[168:171], v[228:231], v[70:73]
	v_mfma_f32_16x16x32_bf16 v[66:69], v[176:179], v[228:231], v[66:69]
	s_setprio 0
	s_barrier
	s_add_u32 s38, s56, s60
	s_addc_u32 s39, s57, s61
	s_add_i32 m0, s97, 0x18000
	ds_read_b128 v[182:185], v147 offset:49152
	ds_read_b128 v[186:189], v147 offset:50176
	ds_read_b128 v[208:211], v147 offset:51200
	ds_read_b128 v[212:215], v147 offset:52224
	ds_read_b128 v[216:219], v147 offset:53248
	ds_read_b128 v[220:223], v147 offset:54272
	ds_read_b128 v[224:227], v147 offset:55296
	ds_read_b128 v[228:231], v147 offset:56320
	global_load_lds_dwordx4 v0, s[38:39]
	s_add_i32 m0, s97, 0x1a000
	s_nop 0
	global_load_lds_dwordx4 v134, s[38:39]
	s_add_i32 m0, s97, 0x1c000
	s_add_u32 s38, s38, s16
	s_addc_u32 s39, s39, 0
	global_load_lds_dwordx4 v0, s[38:39]
	s_add_i32 m0, s97, 0x1e000
	s_nop 0
	global_load_lds_dwordx4 v134, s[38:39]
	s_add_u32 s50, s50, s48
	s_addc_u32 s51, s51, s49
	s_cmp_ge_u32 s80, s13
	s_cselect_b64 vcc, -1, 0
	s_cbranch_scc1 .Lgemm_ctl_done
	s_cmp_eq_u32 s88, s80
	s_cbranch_scc1 .Lgemm_ctl_last
	s_add_u32 s62, s18, s50
	s_addc_u32 s63, s19, s51
	s_add_u32 s56, s87, s50
	s_addc_u32 s57, s33, s51
	s_mov_b64 s[60:61], s[44:45]
	s_branch .Lgemm_ctl_join

; #define PG8_STAGE(bufoff, gbase, voff) do { _Pragma("unroll") for (int _i = 0; _i < 2; ++_i) \
;         __builtin_amdgcn_global_load_lds((const unsigned*)((const char*)(gbase) + (voff)[_i]), (PG8_LAS unsigned*)(lds + (bufoff) + ldsw + _i * 8192), 16, 0, 0); } while (0)
; #define PG8_LDA(dst, b, h) do { _Pragma("unroll") for (int m = 0; m < 4; ++m) _Pragma("unroll") for (int k = 0; k < 2; ++k) dst[m][k] = *(const PG8_LAS bf16x8*)(lds + PG8_SA(b, h) + aoff + m * 2048 + k * 1024); } while (0)
; #define PG8_MMA(ai, bj, At, Bt) do { __builtin_amdgcn_s_setprio(1); _Pragma("unroll") for (int m = 0; m < 4; ++m) _Pragma("unroll") for (int n = 0; n < 2; ++n) _Pragma("unroll") for (int k = 0; k < 2; ++k) \
;         acc[ai][bj][m][n] = __builtin_amdgcn_mfma_f32_16x16x32_bf16(Bt[n][k], At[m][k], acc[ai][bj][m][n], 0, 0, 0); __builtin_amdgcn_s_setprio(0); } while (0)
; #define PG8_WAIT_V(n) asm volatile("s_waitcnt vmcnt(" #n ")" ::: "memory")
; #define PG8_WAIT_L(n) asm volatile("s_waitcnt lgkmcnt(" #n ")" ::: "memory")
; #define PG8_BAR __builtin_amdgcn_s_barrier()
; #define PG8_SCHED __builtin_amdgcn_sched_barrier(0)
; template <class Epi, class Sched, bool ALIGN_EPI = false, bool SP2 = false>
; __device__ __forceinline__ void gemm_phase(PG8_LAS unsigned char* lds, const Gemm g, const Sched& S, const Epi& E) {
;     ...
;             PG8_LDA(At, 1, 1); PG8_STAGE(PG8_SB(1, 0), b3, voffB); PG8_STAGE(PG8_SB(1, 1), b3 + hstep, voffB); PG8_STAGE(PG8_SA(1, 0), a3, voffA);
;             PG8_WAIT_V(8); PG8_WAIT_L(0); PG8_BAR; PG8_MMA(1, 0, At, B0); PG8_MMA(1, 1, At, B1); PG8_BAR; PG8_SCHED;
.Lgemm_ctl_done:
	s_waitcnt vmcnt(6)
	s_waitcnt lgkmcnt(0)
	s_barrier
	s_setprio 1
	s_waitcnt lgkmcnt(0)
	v_mfma_f32_16x16x32_bf16 v[62:65], v[148:151], v[182:185], v[62:65]
	v_mfma_f32_16x16x32_bf16 v[58:61], v[156:159], v[182:185], v[58:61]
	v_mfma_f32_16x16x32_bf16 v[54:57], v[148:151], v[208:211], v[54:57]
	v_mfma_f32_16x16x32_bf16 v[46:49], v[156:159], v[208:211], v[46:49]
	v_mfma_f32_16x16x32_bf16 v[38:41], v[148:151], v[216:219], v[38:41]
	v_mfma_f32_16x16x32_bf16 v[30:33], v[156:159], v[216:219], v[30:33]
	v_mfma_f32_16x16x32_bf16 v[22:25], v[148:151], v[224:227], v[22:25]
	v_mfma_f32_16x16x32_bf16 v[14:17], v[156:159], v[224:227], v[14:17]
	v_mfma_f32_16x16x32_bf16 v[62:65], v[152:155], v[186:189], v[62:65]
	v_mfma_f32_16x16x32_bf16 v[58:61], v[160:163], v[186:189], v[58:61]
	v_mfma_f32_16x16x32_bf16 v[54:57], v[152:155], v[212:215], v[54:57]
	v_mfma_f32_16x16x32_bf16 v[46:49], v[160:163], v[212:215], v[46:49]
	v_mfma_f32_16x16x32_bf16 v[38:41], v[152:155], v[220:223], v[38:41]
	v_mfma_f32_16x16x32_bf16 v[30:33], v[160:163], v[220:223], v[30:33]
	v_mfma_f32_16x16x32_bf16 v[22:25], v[152:155], v[228:231], v[22:25]
	v_mfma_f32_16x16x32_bf16 v[14:17], v[160:163], v[228:231], v[14:17]
	s_setprio 0
	s_setprio 1
	v_mfma_f32_16x16x32_bf16 v[50:53], v[164:167], v[182:185], v[50:53]
	v_mfma_f32_16x16x32_bf16 v[42:45], v[172:175], v[182:185], v[42:45]
	v_mfma_f32_16x16x32_bf16 v[34:37], v[164:167], v[208:211], v[34:37]
	v_mfma_f32_16x16x32_bf16 v[26:29], v[172:175], v[208:211], v[26:29]
	v_mfma_f32_16x16x32_bf16 v[18:21], v[164:167], v[216:219], v[18:21]
	v_mfma_f32_16x16x32_bf16 v[10:13], v[172:175], v[216:219], v[10:13]
	v_mfma_f32_16x16x32_bf16 v[6:9], v[164:167], v[224:227], v[6:9]
	v_mfma_f32_16x16x32_bf16 v[2:5], v[172:175], v[224:227], v[2:5]
	v_mfma_f32_16x16x32_bf16 v[50:53], v[168:171], v[186:189], v[50:53]
	v_mfma_f32_16x16x32_bf16 v[42:45], v[176:179], v[186:189], v[42:45]
	v_mfma_f32_16x16x32_bf16 v[34:37], v[168:171], v[212:215], v[34:37]
	v_mfma_f32_16x16x32_bf16 v[26:29], v[176:179], v[212:215], v[26:29]
	v_mfma_f32_16x16x32_bf16 v[18:21], v[168:171], v[220:223], v[18:21]
	v_mfma_f32_16x16x32_bf16 v[10:13], v[176:179], v[220:223], v[10:13]
	v_mfma_f32_16x16x32_bf16 v[6:9], v[168:171], v[228:231], v[6:9]
	v_mfma_f32_16x16x32_bf16 v[2:5], v[176:179], v[228:231], v[2:5]
	s_setprio 0
	s_barrier
	s_cbranch_vccz .Lgemm_head
	s_branch .LBB0_360
